# comb27 + scan S2 first ladder: one more state-fragment read issued with the initial batch (skip-and-continue hoist), waits re-counted
# speedup vs baseline: 1.0033x; 1.0033x over previous
; #define LAS __attribute__((address_space(3)))
; __device__ __forceinline__ unsigned f2bf(float f) { unsigned u = __builtin_bit_cast(unsigned, f); return (u + 0x7fffu + ((u >> 16) & 1u)) >> 16; }
; __device__ __forceinline__ int scan_row(int b, int dir, int s) { if (s < TC) return b * NT + TL + (dir ? TC - 1 - s : s); const int li = s - TC; return b * NT + (dir ? TL - 1 - li : li); }
; __device__ __forceinline__ void scan_job(LAS unsigned char* lds, int b, int h, int dir, int layer, const bf16_t* P, const float* lbp, bf16_t* xc, bf16_t* ob) {
;     ...
;         { const int ti = wid >> 1, vj0 = 2 * (wid & 1);
;           const LAS unsigned char* pa = lds + S_P + (16 * ti + l15) * 144 + lq * 16; const LAS unsigned char* qa = lds + S_QH + (16 * ti + l15) * 272 + lq * 16;
;           const bf16x8 a0 = *(const LAS bf16x8*)(pa), a1 = *(const LAS bf16x8*)(pa + 64);
;           const bf16x8 q0 = *(const LAS bf16x8*)(qa), q1 = *(const LAS bf16x8*)(qa + 64), q2 = *(const LAS bf16x8*)(qa + 128), q3 = *(const LAS bf16x8*)(qa + 192);
;           const size_t row0 = (size_t)scan_row(b, dir, ch * 64 + 16 * ti + 4 * lq);
; #pragma unroll
;           for (int vv = 0; vv < 2; ++vv) { const int vj = vj0 + vv;
;               const LAS unsigned char* vb = lds + S_VT + (16 * vj + l15) * 144 + lq * 16; const LAS unsigned char* sb = lds + S_ST + (16 * vj + l15) * 272 + lq * 16;
;               f32x4 o = (f32x4){0.f, 0.f, 0.f, 0.f};
;               o = __builtin_amdgcn_mfma_f32_16x16x32_bf16(a0, *(const LAS bf16x8*)(vb), o, 0, 0, 0);
;               o = __builtin_amdgcn_mfma_f32_16x16x32_bf16(a1, *(const LAS bf16x8*)(vb + 64), o, 0, 0, 0);
;               o = __builtin_amdgcn_mfma_f32_16x16x32_bf16(q0, *(const LAS bf16x8*)(sb), o, 0, 0, 0);
;               o = __builtin_amdgcn_mfma_f32_16x16x32_bf16(q1, *(const LAS bf16x8*)(sb + 64), o, 0, 0, 0);
;               o = __builtin_amdgcn_mfma_f32_16x16x32_bf16(q2, *(const LAS bf16x8*)(sb + 128), o, 0, 0, 0);
;               o = __builtin_amdgcn_mfma_f32_16x16x32_bf16(q3, *(const LAS bf16x8*)(sb + 192), o, 0, 0, 0);
;               const int col = h * 64 + 16 * vj + l15;
; #pragma unroll
;               for (int r = 0; r < 4; ++r) { const size_t row = dir ? row0 - r : row0 + r;
;                   if (dir == 0) xc[row * DM + 512 + col] = (bf16_t)f2bf(o[r]); else ob[row * 256 + col] = (bf16_t)f2bf(o[r]); } } }
.LBB0_665:
	s_waitcnt lgkmcnt(0)
	s_barrier
	ds_read_b128 v[38:41], v113
	ds_read_b128 v[22:25], v115
	ds_read_b128 v[42:45], v113 offset:64
	ds_read_b128 v[34:37], v114 offset:17408
	ds_read_b128 v[30:33], v114 offset:17472
	ds_read_b128 v[46:49], v115 offset:64
	ds_read_b128 v[200:203], v116
	s_waitcnt lgkmcnt(5)
	v_mfma_f32_16x16x32_bf16 v[76:79], v[38:41], v[22:25], 0
	ds_read_b128 v[26:29], v114 offset:17536
	ds_read_b128 v[22:25], v114 offset:17600
	v_lshl_add_u32 v130, s72, 6, v107
	v_add_u32_e32 v80, 0xffffff00, v130
	s_waitcnt lgkmcnt(3)
	v_mfma_f32_16x16x32_bf16 v[46:49], v[42:45], v[46:49], v[76:79]
	v_cmp_gt_i32_e32 vcc, s90, v130
	s_mov_b64 s[20:21], -1
	s_nop 0
	v_cndmask_b32_e32 v132, v80, v130, vcc
	ds_read_b128 v[80:83], v116 offset:64
	s_waitcnt lgkmcnt(3)
	v_mfma_f32_16x16x32_bf16 v[46:49], v[34:37], v[200:203], v[46:49]
	ds_read_b128 v[76:79], v116 offset:128
	v_cndmask_b32_e32 v131, v85, v86, vcc
	v_sub_u32_e32 v130, v131, v130
	s_waitcnt lgkmcnt(1)
	v_mfma_f32_16x16x32_bf16 v[46:49], v[30:33], v[80:83], v[46:49]
	v_cndmask_b32_e32 v133, v92, v91, vcc
	v_cndmask_b32_e64 v80, v130, v132, s[2:3]
	v_add_u32_e32 v82, v80, v133
	ds_read_b128 v[130:133], v116 offset:192
	s_waitcnt lgkmcnt(1)
	v_mfma_f32_16x16x32_bf16 v[46:49], v[26:29], v[76:79], v[46:49]
	v_ashrrev_i32_e32 v83, 31, v82
	s_and_b64 vcc, exec, s[54:55]
	s_waitcnt lgkmcnt(0)
	v_mfma_f32_16x16x32_bf16 v[46:49], v[22:25], v[130:133], v[46:49]
	s_nop 7
	v_bfe_u32 v76, v46, 16, 1
	v_add3_u32 v46, v46, v76, s92
	v_lshrrev_b32_e32 v46, 16, v46
	v_lshlrev_b64 v[76:77], 9, v[82:83]
	s_cbranch_vccz .LBB0_667
	v_lshlrev_b64 v[80:81], 9, v[82:83]
	v_lshl_add_u64 v[78:79], v[60:61], 0, v[80:81]
	global_store_short v[78:79], v46, off
	s_mov_b64 s[20:21], 0

; #define LAS __attribute__((address_space(3)))
; __device__ __forceinline__ unsigned f2bf(float f) { unsigned u = __builtin_bit_cast(unsigned, f); return (u + 0x7fffu + ((u >> 16) & 1u)) >> 16; }
; __device__ __forceinline__ int scan_row(int b, int dir, int s) { if (s < TC) return b * NT + TL + (dir ? TC - 1 - s : s); const int li = s - TC; return b * NT + (dir ? TL - 1 - li : li); }
; __device__ __forceinline__ void scan_job(LAS unsigned char* lds, int b, int h, int dir, int layer, const bf16_t* P, const float* lbp, bf16_t* xc, bf16_t* ob) {
;     ...
;         { const int ti = wid >> 1, vj0 = 2 * (wid & 1);
;           const LAS unsigned char* pa = lds + S_P + (16 * ti + l15) * 144 + lq * 16; const LAS unsigned char* qa = lds + S_QH + (16 * ti + l15) * 272 + lq * 16;
;           const bf16x8 a0 = *(const LAS bf16x8*)(pa), a1 = *(const LAS bf16x8*)(pa + 64);
;           const bf16x8 q0 = *(const LAS bf16x8*)(qa), q1 = *(const LAS bf16x8*)(qa + 64), q2 = *(const LAS bf16x8*)(qa + 128), q3 = *(const LAS bf16x8*)(qa + 192);
;           const size_t row0 = (size_t)scan_row(b, dir, ch * 64 + 16 * ti + 4 * lq);
; #pragma unroll
;           for (int vv = 0; vv < 2; ++vv) { const int vj = vj0 + vv;
;               const LAS unsigned char* vb = lds + S_VT + (16 * vj + l15) * 144 + lq * 16; const LAS unsigned char* sb = lds + S_ST + (16 * vj + l15) * 272 + lq * 16;
;               f32x4 o = (f32x4){0.f, 0.f, 0.f, 0.f};
;               o = __builtin_amdgcn_mfma_f32_16x16x32_bf16(a0, *(const LAS bf16x8*)(vb), o, 0, 0, 0);
;               o = __builtin_amdgcn_mfma_f32_16x16x32_bf16(a1, *(const LAS bf16x8*)(vb + 64), o, 0, 0, 0);
;               o = __builtin_amdgcn_mfma_f32_16x16x32_bf16(q0, *(const LAS bf16x8*)(sb), o, 0, 0, 0);
;               o = __builtin_amdgcn_mfma_f32_16x16x32_bf16(q1, *(const LAS bf16x8*)(sb + 64), o, 0, 0, 0);
;               o = __builtin_amdgcn_mfma_f32_16x16x32_bf16(q2, *(const LAS bf16x8*)(sb + 128), o, 0, 0, 0);
;               o = __builtin_amdgcn_mfma_f32_16x16x32_bf16(q3, *(const LAS bf16x8*)(sb + 192), o, 0, 0, 0);
;               const int col = h * 64 + 16 * vj + l15;
; #pragma unroll
;               for (int r = 0; r < 4; ++r) { const size_t row = dir ? row0 - r : row0 + r;
;                   if (dir == 0) xc[row * DM + 512 + col] = (bf16_t)f2bf(o[r]); else ob[row * 256 + col] = (bf16_t)f2bf(o[r]); } } }
.LBB0_1725:
	s_waitcnt lgkmcnt(0)
	s_barrier
	ds_read_b128 v[26:29], v112
	ds_read_b128 v[22:25], v114
	ds_read_b128 v[42:45], v112 offset:64
	ds_read_b128 v[38:41], v113 offset:17408
	ds_read_b128 v[34:37], v113 offset:17472
	ds_read_b128 v[46:49], v114 offset:64
	ds_read_b128 v[200:203], v115
	s_waitcnt lgkmcnt(5)
	v_mfma_f32_16x16x32_bf16 v[76:79], v[26:29], v[22:25], 0
	ds_read_b128 v[30:33], v113 offset:17536
	ds_read_b128 v[22:25], v113 offset:17600
	v_lshl_add_u32 v129, s66, 6, v106
	v_add_u32_e32 v80, 0xffffff00, v129
	s_waitcnt lgkmcnt(3)
	v_mfma_f32_16x16x32_bf16 v[46:49], v[42:45], v[46:49], v[76:79]
	v_cmp_gt_i32_e32 vcc, s87, v129
	s_mov_b64 s[20:21], -1
	s_nop 0
	v_cndmask_b32_e32 v131, v80, v129, vcc
	ds_read_b128 v[80:83], v115 offset:64
	s_waitcnt lgkmcnt(3)
	v_mfma_f32_16x16x32_bf16 v[46:49], v[38:41], v[200:203], v[46:49]
	ds_read_b128 v[76:79], v115 offset:128
	v_cndmask_b32_e32 v130, v84, v85, vcc
	v_sub_u32_e32 v129, v130, v129
	s_waitcnt lgkmcnt(1)
	v_mfma_f32_16x16x32_bf16 v[46:49], v[34:37], v[80:83], v[46:49]
	v_cndmask_b32_e32 v132, v96, v95, vcc
	v_cndmask_b32_e64 v80, v129, v131, s[2:3]
	v_add_u32_e32 v82, v80, v132
	ds_read_b128 v[130:133], v115 offset:192
	s_waitcnt lgkmcnt(1)
	v_mfma_f32_16x16x32_bf16 v[46:49], v[30:33], v[76:79], v[46:49]
	v_ashrrev_i32_e32 v83, 31, v82
	s_and_b64 vcc, exec, s[46:47]
	s_waitcnt lgkmcnt(0)
	v_mfma_f32_16x16x32_bf16 v[46:49], v[22:25], v[130:133], v[46:49]
	s_nop 7
	v_bfe_u32 v76, v46, 16, 1
	v_add3_u32 v46, v46, v76, s89
	v_lshrrev_b32_e32 v46, 16, v46
	v_lshlrev_b64 v[76:77], 9, v[82:83]
	s_cbranch_vccz .LBB0_1727
	v_lshlrev_b64 v[80:81], 9, v[82:83]
	v_lshl_add_u64 v[78:79], v[62:63], 0, v[80:81]
	global_store_short v[78:79], v46, off
	s_mov_b64 s[20:21], 0
